# de-serialized loads in scan2 carry-in, g2 tail reduce and norm2 last-panel partial sums (all issued together, one wait)
# speedup vs baseline: 1.0080x; 1.0080x over previous
; __device__ __forceinline__ void lru_scan2(bf16_t* p5, const bf16_t* bbuf, const float* agg) {
;     ...
;     for (int it = gt; it < NB * NCH64 * 512; it += NGT) {
;         const int cp = it & 511, bc = it >> 9; const int b = bc / NCH64, c = bc - b * NCH64; const size_t m0 = (size_t)b * TP + c * 64;
;         float h0 = 0.f, h1 = 0.f;
;         for (int cc0 = 0; cc0 < c; cc0 += 8) {
;             f32x4 a[8];
; #pragma unroll
;             for (int k = 0; k < 8; ++k) a[k] = (cc0 + k < c) ? *(const f32x4*)(agg + ((size_t)(b * NCH64 + cc0 + k) * 512 + cp) * 4) : (f32x4){0.f, 0.f, 0.f, 0.f};
; #pragma unroll
;             for (int k = 0; k < 8; ++k) { h0 = __expf(a[k].x) * h0 + a[k].y; h1 = __expf(a[k].z) * h1 + a[k].w; }
;         }
.LBB0_947:
	v_ashrrev_i32_e32 v0, 9, v58
	v_mul_hi_i32 v2, v0, s33
	v_lshrrev_b32_e32 v3, 31, v2
	v_ashrrev_i32_e32 v2, 5, v2
	v_add_u32_e32 v60, v2, v3
	v_mul_i32_i24_e32 v40, 0x41, v60
	v_sub_u32_e32 v59, v0, v40
	v_mov_b32_e32 v0, v1
	v_cmp_lt_i32_e32 vcc, 0, v59
	v_mov_b64_e32 v[38:39], v[0:1]
	s_and_saveexec_b64 s[16:17], vcc
	s_cbranch_execz .LBB0_965
	v_readfirstlane_b32 s28, v59
	v_ashrrev_i32_e32 v41, 31, v40
	v_lshlrev_b64 v[2:3], 13, v[40:41]
	v_lshl_add_u64 v[42:43], v[36:37], 0, v[2:3]
	v_mov_b32_e32 v38, 0
	v_mov_b32_e32 v39, 0
	s_mov_b32 s32, 0
	s_mov_b64 s[50:51], 0x2000
.Lc2_loop:
	v_mov_b64_e32 v[44:45], v[42:43]
	global_load_dwordx4 v[64:67], v[44:45], off
	v_lshl_add_u64 v[44:45], v[44:45], 0, s[50:51]
	global_load_dwordx4 v[68:71], v[44:45], off
	v_lshl_add_u64 v[44:45], v[44:45], 0, s[50:51]
	global_load_dwordx4 v[72:75], v[44:45], off
	v_lshl_add_u64 v[44:45], v[44:45], 0, s[50:51]
	global_load_dwordx4 v[76:79], v[44:45], off
	v_lshl_add_u64 v[44:45], v[44:45], 0, s[50:51]
	global_load_dwordx4 v[80:83], v[44:45], off
	v_lshl_add_u64 v[44:45], v[44:45], 0, s[50:51]
	global_load_dwordx4 v[84:87], v[44:45], off
	v_lshl_add_u64 v[44:45], v[44:45], 0, s[50:51]
	global_load_dwordx4 v[88:91], v[44:45], off
	v_lshl_add_u64 v[44:45], v[44:45], 0, s[50:51]
	global_load_dwordx4 v[92:95], v[44:45], off
	v_lshl_add_u64 v[44:45], v[44:45], 0, s[50:51]
	global_load_dwordx4 v[96:99], v[44:45], off
	v_lshl_add_u64 v[44:45], v[44:45], 0, s[50:51]
	global_load_dwordx4 v[100:103], v[44:45], off
	v_lshl_add_u64 v[44:45], v[44:45], 0, s[50:51]
	global_load_dwordx4 v[104:107], v[44:45], off
	v_lshl_add_u64 v[44:45], v[44:45], 0, s[50:51]
	global_load_dwordx4 v[108:111], v[44:45], off
	v_lshl_add_u64 v[44:45], v[44:45], 0, s[50:51]
	global_load_dwordx4 v[112:115], v[44:45], off
	v_lshl_add_u64 v[44:45], v[44:45], 0, s[50:51]
	global_load_dwordx4 v[116:119], v[44:45], off
	v_lshl_add_u64 v[44:45], v[44:45], 0, s[50:51]
	global_load_dwordx4 v[120:123], v[44:45], off
	v_lshl_add_u64 v[44:45], v[44:45], 0, s[50:51]
	global_load_dwordx4 v[124:127], v[44:45], off
	v_lshl_add_u64 v[44:45], v[44:45], 0, s[50:51]
	v_mov_b64_e32 v[42:43], v[44:45]
	s_waitcnt vmcnt(0)
	s_add_u32 s42, s32, 0
	s_cmp_ge_u32 s42, s28
	s_cbranch_scc1 .Lc2_done
	v_mul_f32_e32 v46, 0x3fb8aa3b, v64
	v_exp_f32_e32 v46, v46
	v_mul_f32_e32 v47, 0x3fb8aa3b, v66
	v_exp_f32_e32 v47, v47
	v_fma_f32 v39, v39, v46, v65
	v_fma_f32 v38, v38, v47, v67
	s_add_u32 s42, s32, 1
	s_cmp_ge_u32 s42, s28
	s_cbranch_scc1 .Lc2_done
	v_mul_f32_e32 v46, 0x3fb8aa3b, v68
	v_exp_f32_e32 v46, v46
	v_mul_f32_e32 v47, 0x3fb8aa3b, v70
	v_exp_f32_e32 v47, v47
	v_fma_f32 v39, v39, v46, v69
	v_fma_f32 v38, v38, v47, v71
	s_add_u32 s42, s32, 2
	s_cmp_ge_u32 s42, s28
	s_cbranch_scc1 .Lc2_done
	v_mul_f32_e32 v46, 0x3fb8aa3b, v72
	v_exp_f32_e32 v46, v46
	v_mul_f32_e32 v47, 0x3fb8aa3b, v74
	v_exp_f32_e32 v47, v47
	v_fma_f32 v39, v39, v46, v73
	v_fma_f32 v38, v38, v47, v75
	s_add_u32 s42, s32, 3
	s_cmp_ge_u32 s42, s28
	s_cbranch_scc1 .Lc2_done
	v_mul_f32_e32 v46, 0x3fb8aa3b, v76
	v_exp_f32_e32 v46, v46
	v_mul_f32_e32 v47, 0x3fb8aa3b, v78
	v_exp_f32_e32 v47, v47
	v_fma_f32 v39, v39, v46, v77
	v_fma_f32 v38, v38, v47, v79
	s_add_u32 s42, s32, 4
	s_cmp_ge_u32 s42, s28
	s_cbranch_scc1 .Lc2_done
	v_mul_f32_e32 v46, 0x3fb8aa3b, v80
	v_exp_f32_e32 v46, v46
	v_mul_f32_e32 v47, 0x3fb8aa3b, v82
	v_exp_f32_e32 v47, v47
	v_fma_f32 v39, v39, v46, v81
	v_fma_f32 v38, v38, v47, v83
	s_add_u32 s42, s32, 5
	s_cmp_ge_u32 s42, s28
	s_cbranch_scc1 .Lc2_done
	v_mul_f32_e32 v46, 0x3fb8aa3b, v84
	v_exp_f32_e32 v46, v46
	v_mul_f32_e32 v47, 0x3fb8aa3b, v86
	v_exp_f32_e32 v47, v47
	v_fma_f32 v39, v39, v46, v85
	v_fma_f32 v38, v38, v47, v87
	s_add_u32 s42, s32, 6
	s_cmp_ge_u32 s42, s28
	s_cbranch_scc1 .Lc2_done
	v_mul_f32_e32 v46, 0x3fb8aa3b, v88
	v_exp_f32_e32 v46, v46
	v_mul_f32_e32 v47, 0x3fb8aa3b, v90
	v_exp_f32_e32 v47, v47
	v_fma_f32 v39, v39, v46, v89
	v_fma_f32 v38, v38, v47, v91
	s_add_u32 s42, s32, 7
	s_cmp_ge_u32 s42, s28
	s_cbranch_scc1 .Lc2_done
	v_mul_f32_e32 v46, 0x3fb8aa3b, v92
	v_exp_f32_e32 v46, v46
	v_mul_f32_e32 v47, 0x3fb8aa3b, v94
	v_exp_f32_e32 v47, v47
	v_fma_f32 v39, v39, v46, v93
	v_fma_f32 v38, v38, v47, v95
	s_add_u32 s42, s32, 8
	s_cmp_ge_u32 s42, s28
	s_cbranch_scc1 .Lc2_done
	v_mul_f32_e32 v46, 0x3fb8aa3b, v96
	v_exp_f32_e32 v46, v46
	v_mul_f32_e32 v47, 0x3fb8aa3b, v98
	v_exp_f32_e32 v47, v47
	v_fma_f32 v39, v39, v46, v97
	v_fma_f32 v38, v38, v47, v99
	s_add_u32 s42, s32, 9
	s_cmp_ge_u32 s42, s28
	s_cbranch_scc1 .Lc2_done
	v_mul_f32_e32 v46, 0x3fb8aa3b, v100
	v_exp_f32_e32 v46, v46
	v_mul_f32_e32 v47, 0x3fb8aa3b, v102
	v_exp_f32_e32 v47, v47
	v_fma_f32 v39, v39, v46, v101
	v_fma_f32 v38, v38, v47, v103
	s_add_u32 s42, s32, 10
	s_cmp_ge_u32 s42, s28
	s_cbranch_scc1 .Lc2_done
	v_mul_f32_e32 v46, 0x3fb8aa3b, v104
	v_exp_f32_e32 v46, v46
	v_mul_f32_e32 v47, 0x3fb8aa3b, v106
	v_exp_f32_e32 v47, v47
	v_fma_f32 v39, v39, v46, v105
	v_fma_f32 v38, v38, v47, v107
	s_add_u32 s42, s32, 11
	s_cmp_ge_u32 s42, s28
	s_cbranch_scc1 .Lc2_done
	v_mul_f32_e32 v46, 0x3fb8aa3b, v108
	v_exp_f32_e32 v46, v46
	v_mul_f32_e32 v47, 0x3fb8aa3b, v110
	v_exp_f32_e32 v47, v47
	v_fma_f32 v39, v39, v46, v109
	v_fma_f32 v38, v38, v47, v111
	s_add_u32 s42, s32, 12
	s_cmp_ge_u32 s42, s28
	s_cbranch_scc1 .Lc2_done
	v_mul_f32_e32 v46, 0x3fb8aa3b, v112
	v_exp_f32_e32 v46, v46
	v_mul_f32_e32 v47, 0x3fb8aa3b, v114
	v_exp_f32_e32 v47, v47
	v_fma_f32 v39, v39, v46, v113
	v_fma_f32 v38, v38, v47, v115
	s_add_u32 s42, s32, 13
	s_cmp_ge_u32 s42, s28
	s_cbranch_scc1 .Lc2_done
	v_mul_f32_e32 v46, 0x3fb8aa3b, v116
	v_exp_f32_e32 v46, v46
	v_mul_f32_e32 v47, 0x3fb8aa3b, v118
	v_exp_f32_e32 v47, v47
	v_fma_f32 v39, v39, v46, v117
	v_fma_f32 v38, v38, v47, v119
	s_add_u32 s42, s32, 14
	s_cmp_ge_u32 s42, s28
	s_cbranch_scc1 .Lc2_done
	v_mul_f32_e32 v46, 0x3fb8aa3b, v120
	v_exp_f32_e32 v46, v46
	v_mul_f32_e32 v47, 0x3fb8aa3b, v122
	v_exp_f32_e32 v47, v47
	v_fma_f32 v39, v39, v46, v121
	v_fma_f32 v38, v38, v47, v123
	s_add_u32 s42, s32, 15
	s_cmp_ge_u32 s42, s28
	s_cbranch_scc1 .Lc2_done
	v_mul_f32_e32 v46, 0x3fb8aa3b, v124
	v_exp_f32_e32 v46, v46
	v_mul_f32_e32 v47, 0x3fb8aa3b, v126
	v_exp_f32_e32 v47, v47
	v_fma_f32 v39, v39, v46, v125
	v_fma_f32 v38, v38, v47, v127
	s_add_u32 s32, s32, 16
	s_cmp_lt_u32 s32, s28
	s_cbranch_scc1 .Lc2_loop
.Lc2_done:
.LBB0_965:
	s_or_b64 exec, exec, s[16:17]
	v_mul_i32_i24_e32 v2, 0x1040, v60
	v_lshlrev_b32_e32 v4, 6, v59
	v_ashrrev_i32_e32 v3, 31, v2
	v_ashrrev_i32_e32 v5, 31, v4
	v_lshl_add_u64 v[4:5], v[4:5], 0, v[2:3]
	v_mov_b64_e32 v[2:3], s[0:1]
	v_mad_u64_u32 v[2:3], s[16:17], v4, s84, v[2:3]
	v_mad_i32_i24 v3, v5, s84, v3
	v_lshlrev_b64 v[4:5], 11, v[4:5]
	v_lshl_add_u64 v[4:5], s[0:1], 0, v[4:5]
	s_mov_b32 s16, -8

; __device__ __forceinline__ int opaque_tid() { int t = threadIdx.x; asm volatile("" : "+v"(t)); return t; }
; __device__ __forceinline__ unsigned cvt_pk_bf16(float lo, float hi) { unsigned r; asm volatile("v_cvt_pk_bf16_f32 %0, %1, %2" : "=v"(r) : "v"(lo), "v"(hi)); return r; }
; __device__ __forceinline__ void g2_tail_reduce(const float* part, int pieces, bf16_t* merged) {
;     const int tid = opaque_tid(); const int pn = (4 * tid) >> 8, cc = (4 * tid) & 255;
;     for (int R = blockIdx.x; R < 256; R += gridDim.x) {
;         f32x4 a = (f32x4){0.f, 0.f, 0.f, 0.f};
;         for (int k = 0; k < 3 * pieces; ++k) a += *(const f32x4*)(part + (size_t)(pn * 3 * pieces + k) * 65536 + (size_t)R * 256 + cc);
;         *(u32x2*)(merged + (size_t)(MP - 256 + R) * D + 4 * tid) = (u32x2){cvt_pk_bf16(a.x, a.y), cvt_pk_bf16(a.z, a.w)};
;     }
; }
.LBB0_1352:
	s_ashr_i32 s1, s0, 31
	s_lshl_b64 s[4:5], s[0:1], 10
	v_lshl_add_u64 v[34:35], v[2:3], 0, s[4:5]
	v_lshl_add_u64 v[114:115], v[34:35], 0, v[6:7]
	global_load_dwordx4 v[66:69], v[114:115], off
	v_lshl_add_u64 v[114:115], v[34:35], 0, v[8:9]
	global_load_dwordx4 v[70:73], v[114:115], off
	v_lshl_add_u64 v[114:115], v[34:35], 0, v[10:11]
	global_load_dwordx4 v[74:77], v[114:115], off
	v_lshl_add_u64 v[114:115], v[34:35], 0, v[12:13]
	global_load_dwordx4 v[78:81], v[114:115], off
	v_lshl_add_u64 v[114:115], v[34:35], 0, v[14:15]
	global_load_dwordx4 v[82:85], v[114:115], off
	v_lshl_add_u64 v[114:115], v[34:35], 0, v[16:17]
	global_load_dwordx4 v[86:89], v[114:115], off
	v_lshl_add_u64 v[114:115], v[34:35], 0, v[18:19]
	global_load_dwordx4 v[90:93], v[114:115], off
	v_lshl_add_u64 v[114:115], v[34:35], 0, v[20:21]
	global_load_dwordx4 v[94:97], v[114:115], off
	v_lshl_add_u64 v[114:115], v[34:35], 0, v[22:23]
	global_load_dwordx4 v[98:101], v[114:115], off
	v_lshl_add_u64 v[114:115], v[34:35], 0, v[24:25]
	global_load_dwordx4 v[102:105], v[114:115], off
	v_lshl_add_u64 v[114:115], v[34:35], 0, v[26:27]
	global_load_dwordx4 v[106:109], v[114:115], off
	v_lshl_add_u64 v[114:115], v[34:35], 0, v[28:29]
	global_load_dwordx4 v[110:113], v[114:115], off
	s_add_i32 s4, s0, 0x4000
	s_ashr_i32 s5, s4, 31
	s_lshl_b64 s[4:5], s[4:5], 12
	s_add_i32 s0, s0, s64
	s_cmpk_lt_i32 s0, 0x100
	s_waitcnt vmcnt(0)
	v_pk_add_f32 v[38:39], v[66:67], 0 op_sel_hi:[1,0]
	v_pk_add_f32 v[36:37], v[68:69], 0 op_sel_hi:[1,0]
	v_pk_add_f32 v[38:39], v[38:39], v[70:71]
	v_pk_add_f32 v[36:37], v[36:37], v[72:73]
	v_pk_add_f32 v[38:39], v[38:39], v[74:75]
	v_pk_add_f32 v[36:37], v[36:37], v[76:77]
	v_pk_add_f32 v[38:39], v[38:39], v[78:79]
	v_pk_add_f32 v[36:37], v[36:37], v[80:81]
	v_pk_add_f32 v[38:39], v[38:39], v[82:83]
	v_pk_add_f32 v[36:37], v[36:37], v[84:85]
	v_pk_add_f32 v[38:39], v[38:39], v[86:87]
	v_pk_add_f32 v[36:37], v[36:37], v[88:89]
	v_pk_add_f32 v[38:39], v[38:39], v[90:91]
	v_pk_add_f32 v[36:37], v[36:37], v[92:93]
	v_pk_add_f32 v[38:39], v[38:39], v[94:95]
	v_pk_add_f32 v[36:37], v[36:37], v[96:97]
	v_pk_add_f32 v[38:39], v[38:39], v[98:99]
	v_pk_add_f32 v[36:37], v[36:37], v[100:101]
	v_pk_add_f32 v[38:39], v[38:39], v[102:103]
	v_pk_add_f32 v[36:37], v[36:37], v[104:105]
	v_pk_add_f32 v[38:39], v[38:39], v[106:107]
	v_pk_add_f32 v[36:37], v[36:37], v[108:109]
	v_pk_add_f32 v[38:39], v[38:39], v[110:111]
	v_pk_add_f32 v[36:37], v[36:37], v[112:113]
	s_nop 0
	v_cvt_pk_bf16_f32 v30, v38, v39
	v_cvt_pk_bf16_f32 v31, v36, v37
	v_lshl_add_u64 v[32:33], v[4:5], 0, s[4:5]
	global_store_dwordx2 v[32:33], v[30:31], off
	s_cbranch_scc1 .LBB0_1352

; __device__ __forceinline__ void phase_norm(const Params& P, int mode, const bf16_t* src, const float* w_add, const float* w_norm, bf16_t* hbuf, bf16_t* xsb, const float* part, int pieces) {
;     ...
;             } else {
; #pragma unroll
;                 for (int j = 0; j < 8; ++j) s[j] = (f32x4){0.f, 0.f, 0.f, 0.f};
; #pragma unroll 2
;                 for (int pc = 0; pc < pieces; ++pc) {
; #pragma unroll
;                     for (int j = 0; j < 8; ++j) s[j] += ((const f32x4*)(part + ((size_t)(j * pieces + pc) * 256 + (m - (MP - 256))) * 256))[lane];
;                 }
;             }
.LBB0_1566:
	v_lshl_add_u64 v[118:119], v[116:117], 0, s[18:19]
	s_mov_b64 s[44:45], 0x21000000
	v_lshl_add_u64 v[156:157], v[118:119], 0, s[44:45]
	global_load_dwordx4 v[124:127], v[156:157], off
	s_mov_b64 s[44:45], 0x21100000
	v_lshl_add_u64 v[156:157], v[118:119], 0, s[44:45]
	global_load_dwordx4 v[128:131], v[156:157], off
	s_mov_b64 s[44:45], 0x21200000
	v_lshl_add_u64 v[156:157], v[118:119], 0, s[44:45]
	global_load_dwordx4 v[132:135], v[156:157], off
	s_mov_b64 s[44:45], 0x21300000
	v_lshl_add_u64 v[156:157], v[118:119], 0, s[44:45]
	global_load_dwordx4 v[136:139], v[156:157], off
	s_mov_b64 s[44:45], 0x21400000
	v_lshl_add_u64 v[156:157], v[118:119], 0, s[44:45]
	global_load_dwordx4 v[140:143], v[156:157], off
	s_mov_b64 s[44:45], 0x21500000
	v_lshl_add_u64 v[156:157], v[118:119], 0, s[44:45]
	global_load_dwordx4 v[144:147], v[156:157], off
	s_mov_b64 s[44:45], 0x21600000
	v_lshl_add_u64 v[156:157], v[118:119], 0, s[44:45]
	global_load_dwordx4 v[148:151], v[156:157], off
	s_mov_b64 s[44:45], 0x21700000
	v_lshl_add_u64 v[156:157], v[118:119], 0, s[44:45]
	global_load_dwordx4 v[152:155], v[156:157], off
	s_mov_b64 s[44:45], 0x21040000
	v_lshl_add_u64 v[156:157], v[118:119], 0, s[44:45]
	global_load_dwordx4 v[166:169], v[156:157], off
	s_mov_b64 s[44:45], 0x21140000
	v_lshl_add_u64 v[156:157], v[118:119], 0, s[44:45]
	global_load_dwordx4 v[170:173], v[156:157], off
	s_mov_b64 s[44:45], 0x21240000
	v_lshl_add_u64 v[156:157], v[118:119], 0, s[44:45]
	global_load_dwordx4 v[174:177], v[156:157], off
	s_mov_b64 s[44:45], 0x21340000
	v_lshl_add_u64 v[156:157], v[118:119], 0, s[44:45]
	global_load_dwordx4 v[178:181], v[156:157], off
	s_mov_b64 s[44:45], 0x21440000
	v_lshl_add_u64 v[156:157], v[118:119], 0, s[44:45]
	global_load_dwordx4 v[182:185], v[156:157], off
	s_mov_b64 s[44:45], 0x21540000
	v_lshl_add_u64 v[156:157], v[118:119], 0, s[44:45]
	global_load_dwordx4 v[186:189], v[156:157], off
	s_mov_b64 s[44:45], 0x21640000
	v_lshl_add_u64 v[156:157], v[118:119], 0, s[44:45]
	global_load_dwordx4 v[190:193], v[156:157], off
	s_mov_b64 s[44:45], 0x21740000
	v_lshl_add_u64 v[156:157], v[118:119], 0, s[44:45]
	global_load_dwordx4 v[194:197], v[156:157], off
	s_add_u32 s18, s18, 0x80000
	s_addc_u32 s19, s19, 0
	s_cmp_lg_u32 s18, 0x100000
	s_waitcnt vmcnt(0)
	v_pk_add_f32 v[62:63], v[62:63], v[124:125]
	v_pk_add_f32 v[64:65], v[64:65], v[126:127]
	v_pk_add_f32 v[58:59], v[58:59], v[128:129]
	v_pk_add_f32 v[60:61], v[60:61], v[130:131]
	v_pk_add_f32 v[54:55], v[54:55], v[132:133]
	v_pk_add_f32 v[56:57], v[56:57], v[134:135]
	v_pk_add_f32 v[50:51], v[50:51], v[136:137]
	v_pk_add_f32 v[52:53], v[52:53], v[138:139]
	v_pk_add_f32 v[46:47], v[46:47], v[140:141]
	v_pk_add_f32 v[48:49], v[48:49], v[142:143]
	v_pk_add_f32 v[42:43], v[42:43], v[144:145]
	v_pk_add_f32 v[44:45], v[44:45], v[146:147]
	v_pk_add_f32 v[38:39], v[38:39], v[148:149]
	v_pk_add_f32 v[40:41], v[40:41], v[150:151]
	v_pk_add_f32 v[34:35], v[34:35], v[152:153]
	v_pk_add_f32 v[36:37], v[36:37], v[154:155]
	v_pk_add_f32 v[62:63], v[62:63], v[166:167]
	v_pk_add_f32 v[64:65], v[64:65], v[168:169]
	v_pk_add_f32 v[58:59], v[58:59], v[170:171]
	v_pk_add_f32 v[60:61], v[60:61], v[172:173]
	v_pk_add_f32 v[54:55], v[54:55], v[174:175]
	v_pk_add_f32 v[56:57], v[56:57], v[176:177]
	v_pk_add_f32 v[50:51], v[50:51], v[178:179]
	v_pk_add_f32 v[52:53], v[52:53], v[180:181]
	v_pk_add_f32 v[46:47], v[46:47], v[182:183]
	v_pk_add_f32 v[48:49], v[48:49], v[184:185]
	v_pk_add_f32 v[42:43], v[42:43], v[186:187]
	v_pk_add_f32 v[44:45], v[44:45], v[188:189]
	v_pk_add_f32 v[38:39], v[38:39], v[190:191]
	v_pk_add_f32 v[40:41], v[40:41], v[192:193]
	v_pk_add_f32 v[34:35], v[34:35], v[194:195]
	v_pk_add_f32 v[36:37], v[36:37], v[196:197]
	s_cbranch_scc1 .LBB0_1566
	s_mov_b32 s24, s28
